# residual-add GEMM epilogues: 14-deep pipelined global loads/stores instead of serialized load-wait-store
# baseline (speedup 1.0000x reference)
; #define lds fresh_lds(lds0)
;     DI void operator()(const Acc& acc, const Unit& u, int wr, int wc, int fr, int fq) const {
;         const int row0 = u.pm * BM + wr * 64 + fr, col0 = u.pn * BM + wc * 32 + 4 * fq;
; #pragma unroll
;         for (int ai = 0; ai < 2; ++ai)
; #pragma unroll
;             for (int m = 0; m < 4; ++m) {
;                 const size_t off = (size_t)(row0 + ai * HALF + m * 16) * ldc + col0;
; #pragma unroll
;                 for (int bj = 0; bj < 2; ++bj)
; #pragma unroll
;                     for (int n = 0; n < 2; ++n) { const f32x4 b = *(const f32x4*)(base + off + bj * HALF + n * 16); *(f32x4*)(out + off + bj * HALF + n * 16) = b + acc[ai][bj][m][n] * alpha; }
;                 asm volatile("" ::: "memory");
;             }
;     }
; DI void ffn_gemms(LAS unsigned char* lds, cg::grid_group& grid, unsigned char* ws, const float* base, float* X, int G, int bid, int wv0) {
;     ...
;     { pg8::Gemm g{ACT, Wd, MTOK, DM, DFF, DFF, DFF}; pg8::StaticOrder S; S.init(MTOK, DM, G, bid); pg8::EpiResid E{rep == 0 ? base : X, X, DM, rep == 0 ? 0.5f : 0.f}; pg8::gemm_phase(lds, g, S, E, wv0); }
.LBB0_488:
	v_mov_b32_e32 v136, v1
	s_lshl_b32 s0, s47, 8
	v_mbcnt_lo_u32_b32 v136, -1, v136
	v_mbcnt_hi_u32_b32 v136, -1, v136
	s_add_i32 s0, s0, s28
	v_and_or_b32 v140, v136, 15, s0
	s_lshl_b32 s0, s48, 8
	v_lshrrev_b32_e32 v136, 2, v136
	v_and_or_b32 v136, v136, 12, s0
	v_or_b32_e32 v138, s29, v136
	v_lshlrev_b32_e32 v140, 12, v140
	v_lshl_add_u32 v136, v138, 2, v140
	v_add_u32_e32 v137, 0x10000, v136
	v_add_u32_e32 v138, 0x20000, v136
	v_add_u32_e32 v139, 0x30000, v136
	v_add_u32_e32 v140, 0x80000, v136
	v_add_u32_e32 v141, 0x90000, v136
	v_add_u32_e32 v144, 0xa0000, v136
	v_add_u32_e32 v145, 0xb0000, v136
	global_load_dwordx4 v[146:149], v136, s[36:37]
	global_load_dwordx4 v[150:153], v136, s[36:37] offset:64
	global_load_dwordx4 v[178:181], v136, s[36:37] offset:512
	global_load_dwordx4 v[182:185], v136, s[36:37] offset:576
	global_load_dwordx4 v[186:189], v137, s[36:37]
	global_load_dwordx4 v[190:193], v137, s[36:37] offset:64
	global_load_dwordx4 v[194:197], v137, s[36:37] offset:512
	global_load_dwordx4 v[210:213], v137, s[36:37] offset:576
	global_load_dwordx4 v[214:217], v138, s[36:37]
	global_load_dwordx4 v[218:221], v138, s[36:37] offset:64
	global_load_dwordx4 v[222:225], v138, s[36:37] offset:512
	global_load_dwordx4 v[226:229], v138, s[36:37] offset:576
	global_load_dwordx4 v[230:233], v139, s[36:37]
	global_load_dwordx4 v[234:237], v139, s[36:37] offset:64
	s_waitcnt vmcnt(13)
	v_pk_fma_f32 v[128:129], v[128:129], 0.5, v[148:149] op_sel_hi:[1,0,1]
	v_pk_fma_f32 v[126:127], v[126:127], 0.5, v[146:147] op_sel_hi:[1,0,1]
	global_store_dwordx4 v136, v[126:129], s[34:35]
	global_load_dwordx4 v[146:149], v139, s[36:37] offset:512
	s_waitcnt vmcnt(14)
	v_pk_fma_f32 v[124:125], v[124:125], 0.5, v[152:153] op_sel_hi:[1,0,1]
	v_pk_fma_f32 v[122:123], v[122:123], 0.5, v[150:151] op_sel_hi:[1,0,1]
	global_store_dwordx4 v136, v[122:125], s[34:35] offset:64
	global_load_dwordx4 v[150:153], v139, s[36:37] offset:576
	s_waitcnt vmcnt(15)
	v_pk_fma_f32 v[120:121], v[120:121], 0.5, v[180:181] op_sel_hi:[1,0,1]
	v_pk_fma_f32 v[118:119], v[118:119], 0.5, v[178:179] op_sel_hi:[1,0,1]
	global_store_dwordx4 v136, v[118:121], s[34:35] offset:512
	global_load_dwordx4 v[178:181], v140, s[36:37]
	s_waitcnt vmcnt(16)
	v_pk_fma_f32 v[116:117], v[116:117], 0.5, v[184:185] op_sel_hi:[1,0,1]
	v_pk_fma_f32 v[114:115], v[114:115], 0.5, v[182:183] op_sel_hi:[1,0,1]
	global_store_dwordx4 v136, v[114:117], s[34:35] offset:576
	global_load_dwordx4 v[182:185], v140, s[36:37] offset:64
	s_waitcnt vmcnt(17)
	v_pk_fma_f32 v[112:113], v[112:113], 0.5, v[188:189] op_sel_hi:[1,0,1]
	v_pk_fma_f32 v[110:111], v[110:111], 0.5, v[186:187] op_sel_hi:[1,0,1]
	global_store_dwordx4 v137, v[110:113], s[34:35]
	global_load_dwordx4 v[186:189], v140, s[36:37] offset:512
	s_waitcnt vmcnt(18)
	v_pk_fma_f32 v[108:109], v[108:109], 0.5, v[192:193] op_sel_hi:[1,0,1]
	v_pk_fma_f32 v[106:107], v[106:107], 0.5, v[190:191] op_sel_hi:[1,0,1]
	global_store_dwordx4 v137, v[106:109], s[34:35] offset:64
	global_load_dwordx4 v[190:193], v140, s[36:37] offset:576
	s_waitcnt vmcnt(19)
	v_pk_fma_f32 v[104:105], v[104:105], 0.5, v[196:197] op_sel_hi:[1,0,1]
	v_pk_fma_f32 v[102:103], v[102:103], 0.5, v[194:195] op_sel_hi:[1,0,1]
	global_store_dwordx4 v137, v[102:105], s[34:35] offset:512
	global_load_dwordx4 v[194:197], v141, s[36:37]
	s_waitcnt vmcnt(20)
	v_pk_fma_f32 v[100:101], v[100:101], 0.5, v[212:213] op_sel_hi:[1,0,1]
	v_pk_fma_f32 v[98:99], v[98:99], 0.5, v[210:211] op_sel_hi:[1,0,1]
	global_store_dwordx4 v137, v[98:101], s[34:35] offset:576
	global_load_dwordx4 v[210:213], v141, s[36:37] offset:64
	s_waitcnt vmcnt(21)
	v_pk_fma_f32 v[96:97], v[96:97], 0.5, v[216:217] op_sel_hi:[1,0,1]
	v_pk_fma_f32 v[94:95], v[94:95], 0.5, v[214:215] op_sel_hi:[1,0,1]
	global_store_dwordx4 v138, v[94:97], s[34:35]
	global_load_dwordx4 v[214:217], v141, s[36:37] offset:512
	s_waitcnt vmcnt(22)
	v_pk_fma_f32 v[92:93], v[92:93], 0.5, v[220:221] op_sel_hi:[1,0,1]
	v_pk_fma_f32 v[90:91], v[90:91], 0.5, v[218:219] op_sel_hi:[1,0,1]
	global_store_dwordx4 v138, v[90:93], s[34:35] offset:64
	global_load_dwordx4 v[218:221], v141, s[36:37] offset:576
	s_waitcnt vmcnt(23)
	v_pk_fma_f32 v[88:89], v[88:89], 0.5, v[224:225] op_sel_hi:[1,0,1]
	v_pk_fma_f32 v[86:87], v[86:87], 0.5, v[222:223] op_sel_hi:[1,0,1]
	global_store_dwordx4 v138, v[86:89], s[34:35] offset:512
	global_load_dwordx4 v[222:225], v144, s[36:37]
	s_waitcnt vmcnt(24)
	v_pk_fma_f32 v[84:85], v[84:85], 0.5, v[228:229] op_sel_hi:[1,0,1]
	v_pk_fma_f32 v[82:83], v[82:83], 0.5, v[226:227] op_sel_hi:[1,0,1]
	global_store_dwordx4 v138, v[82:85], s[34:35] offset:576
	global_load_dwordx4 v[226:229], v144, s[36:37] offset:64
	s_waitcnt vmcnt(25)
;     DI void operator()(const Acc& acc, const Unit& u, int wr, int wc, int fr, int fq) const {
;         const int row0 = u.pm * BM + wr * 64 + fr, col0 = u.pn * BM + wc * 32 + 4 * fq;
; #pragma unroll
;         for (int ai = 0; ai < 2; ++ai)
; #pragma unroll
;             for (int m = 0; m < 4; ++m) {
;                 const size_t off = (size_t)(row0 + ai * HALF + m * 16) * ldc + col0;
; #pragma unroll
;                 for (int bj = 0; bj < 2; ++bj)
; #pragma unroll
;                     for (int n = 0; n < 2; ++n) { const f32x4 b = *(const f32x4*)(base + off + bj * HALF + n * 16); *(f32x4*)(out + off + bj * HALF + n * 16) = b + acc[ai][bj][m][n] * alpha; }
;                 asm volatile("" ::: "memory");
;             }
;     }
	v_pk_fma_f32 v[80:81], v[80:81], 0.5, v[232:233] op_sel_hi:[1,0,1]
	v_pk_fma_f32 v[78:79], v[78:79], 0.5, v[230:231] op_sel_hi:[1,0,1]
	global_store_dwordx4 v139, v[78:81], s[34:35]
	global_load_dwordx4 v[230:233], v144, s[36:37] offset:512
	s_waitcnt vmcnt(26)
	v_pk_fma_f32 v[76:77], v[76:77], 0.5, v[236:237] op_sel_hi:[1,0,1]
	v_pk_fma_f32 v[74:75], v[74:75], 0.5, v[234:235] op_sel_hi:[1,0,1]
	global_store_dwordx4 v139, v[74:77], s[34:35] offset:64
	global_load_dwordx4 v[234:237], v144, s[36:37] offset:576
	s_waitcnt vmcnt(26)
	v_pk_fma_f32 v[72:73], v[72:73], 0.5, v[148:149] op_sel_hi:[1,0,1]
	v_pk_fma_f32 v[70:71], v[70:71], 0.5, v[146:147] op_sel_hi:[1,0,1]
	global_store_dwordx4 v139, v[70:73], s[34:35] offset:512
	global_load_dwordx4 v[146:149], v145, s[36:37]
	s_waitcnt vmcnt(26)
	v_pk_fma_f32 v[68:69], v[68:69], 0.5, v[152:153] op_sel_hi:[1,0,1]
	v_pk_fma_f32 v[66:67], v[66:67], 0.5, v[150:151] op_sel_hi:[1,0,1]
	global_store_dwordx4 v139, v[66:69], s[34:35] offset:576
	global_load_dwordx4 v[150:153], v145, s[36:37] offset:64
	s_waitcnt vmcnt(26)
	v_pk_fma_f32 v[64:65], v[64:65], 0.5, v[180:181] op_sel_hi:[1,0,1]
	v_pk_fma_f32 v[62:63], v[62:63], 0.5, v[178:179] op_sel_hi:[1,0,1]
	global_store_dwordx4 v140, v[62:65], s[34:35]
	global_load_dwordx4 v[178:181], v145, s[36:37] offset:512
	s_waitcnt vmcnt(26)
	v_pk_fma_f32 v[60:61], v[60:61], 0.5, v[184:185] op_sel_hi:[1,0,1]
	v_pk_fma_f32 v[58:59], v[58:59], 0.5, v[182:183] op_sel_hi:[1,0,1]
	global_store_dwordx4 v140, v[58:61], s[34:35] offset:64
	global_load_dwordx4 v[182:185], v145, s[36:37] offset:576
	s_waitcnt vmcnt(26)
	v_pk_fma_f32 v[56:57], v[56:57], 0.5, v[188:189] op_sel_hi:[1,0,1]
	v_pk_fma_f32 v[54:55], v[54:55], 0.5, v[186:187] op_sel_hi:[1,0,1]
	global_store_dwordx4 v140, v[54:57], s[34:35] offset:512
	s_waitcnt vmcnt(25)
	v_pk_fma_f32 v[52:53], v[52:53], 0.5, v[192:193] op_sel_hi:[1,0,1]
	v_pk_fma_f32 v[50:51], v[50:51], 0.5, v[190:191] op_sel_hi:[1,0,1]
	global_store_dwordx4 v140, v[50:53], s[34:35] offset:576
	s_waitcnt vmcnt(24)
	v_pk_fma_f32 v[48:49], v[48:49], 0.5, v[196:197] op_sel_hi:[1,0,1]
	v_pk_fma_f32 v[46:47], v[46:47], 0.5, v[194:195] op_sel_hi:[1,0,1]
	global_store_dwordx4 v141, v[46:49], s[34:35]
	s_waitcnt vmcnt(23)
	v_pk_fma_f32 v[44:45], v[44:45], 0.5, v[212:213] op_sel_hi:[1,0,1]
	v_pk_fma_f32 v[42:43], v[42:43], 0.5, v[210:211] op_sel_hi:[1,0,1]
	global_store_dwordx4 v141, v[42:45], s[34:35] offset:64
	s_waitcnt vmcnt(22)
	v_pk_fma_f32 v[40:41], v[40:41], 0.5, v[216:217] op_sel_hi:[1,0,1]
	v_pk_fma_f32 v[38:39], v[38:39], 0.5, v[214:215] op_sel_hi:[1,0,1]
	global_store_dwordx4 v141, v[38:41], s[34:35] offset:512
	s_waitcnt vmcnt(21)
	v_pk_fma_f32 v[36:37], v[36:37], 0.5, v[220:221] op_sel_hi:[1,0,1]
	v_pk_fma_f32 v[34:35], v[34:35], 0.5, v[218:219] op_sel_hi:[1,0,1]
	global_store_dwordx4 v141, v[34:37], s[34:35] offset:576
	s_waitcnt vmcnt(20)
	v_pk_fma_f32 v[32:33], v[32:33], 0.5, v[224:225] op_sel_hi:[1,0,1]
	v_pk_fma_f32 v[30:31], v[30:31], 0.5, v[222:223] op_sel_hi:[1,0,1]
	global_store_dwordx4 v144, v[30:33], s[34:35]
	s_waitcnt vmcnt(19)
	v_pk_fma_f32 v[28:29], v[28:29], 0.5, v[228:229] op_sel_hi:[1,0,1]
	v_pk_fma_f32 v[26:27], v[26:27], 0.5, v[226:227] op_sel_hi:[1,0,1]
	global_store_dwordx4 v144, v[26:29], s[34:35] offset:64
	s_waitcnt vmcnt(18)
	v_pk_fma_f32 v[24:25], v[24:25], 0.5, v[232:233] op_sel_hi:[1,0,1]
	v_pk_fma_f32 v[22:23], v[22:23], 0.5, v[230:231] op_sel_hi:[1,0,1]
	global_store_dwordx4 v144, v[22:25], s[34:35] offset:512
	s_waitcnt vmcnt(17)
	v_pk_fma_f32 v[20:21], v[20:21], 0.5, v[236:237] op_sel_hi:[1,0,1]
	v_pk_fma_f32 v[18:19], v[18:19], 0.5, v[234:235] op_sel_hi:[1,0,1]
	global_store_dwordx4 v144, v[18:21], s[34:35] offset:576
	s_waitcnt vmcnt(16)
	v_pk_fma_f32 v[16:17], v[16:17], 0.5, v[148:149] op_sel_hi:[1,0,1]
	v_pk_fma_f32 v[14:15], v[14:15], 0.5, v[146:147] op_sel_hi:[1,0,1]
	global_store_dwordx4 v145, v[14:17], s[34:35]
	s_waitcnt vmcnt(15)
	v_pk_fma_f32 v[12:13], v[12:13], 0.5, v[152:153] op_sel_hi:[1,0,1]
	v_pk_fma_f32 v[10:11], v[10:11], 0.5, v[150:151] op_sel_hi:[1,0,1]
	global_store_dwordx4 v145, v[10:13], s[34:35] offset:64
	s_waitcnt vmcnt(14)
	v_pk_fma_f32 v[8:9], v[8:9], 0.5, v[180:181] op_sel_hi:[1,0,1]
	v_pk_fma_f32 v[6:7], v[6:7], 0.5, v[178:179] op_sel_hi:[1,0,1]
	global_store_dwordx4 v145, v[6:9], s[34:35] offset:512
	s_waitcnt vmcnt(13)
	v_pk_fma_f32 v[4:5], v[4:5], 0.5, v[184:185] op_sel_hi:[1,0,1]
	v_pk_fma_f32 v[2:3], v[2:3], 0.5, v[182:183] op_sel_hi:[1,0,1]
	global_store_dwordx4 v145, v[2:5], s[34:35] offset:576
	s_mov_b64 s[0:1], -1
	s_and_b64 vcc, exec, s[2:3]
	s_cbranch_vccnz .LBB0_473
	s_andn2_b64 vcc, exec, s[6:7]
	s_cbranch_vccnz .LBB0_472
	s_barrier
	s_branch .LBB0_472

; #define lds fresh_lds(lds0)
;     DI void operator()(const Acc& acc, const Unit& u, int wr, int wc, int fr, int fq) const {
;         const int row0 = u.pm * BM + wr * 64 + fr, col0 = u.pn * BM + wc * 32 + 4 * fq;
; #pragma unroll
;         for (int ai = 0; ai < 2; ++ai)
; #pragma unroll
;             for (int m = 0; m < 4; ++m) {
;                 const size_t off = (size_t)(row0 + ai * HALF + m * 16) * ldc + col0;
; #pragma unroll
;                 for (int bj = 0; bj < 2; ++bj)
; #pragma unroll
;                     for (int n = 0; n < 2; ++n) { const f32x4 b = *(const f32x4*)(base + off + bj * HALF + n * 16); *(f32x4*)(out + off + bj * HALF + n * 16) = b + acc[ai][bj][m][n] * alpha; }
;                 asm volatile("" ::: "memory");
;             }
;     }
; __global__ void __launch_bounds__(512) mega_fwd(Params P) {
;     ...
;         { PHASE_PTRS; pg8::Gemm g{HN, Wout, MTOK, DM, DM, DM, DM}; pg8::StaticOrder S; S.init(MTOK, DM, G, bid); pg8::EpiResid E{X, X, DM, 1.0f}; pg8::gemm_phase(lds, g, S, E, wv0); }
.LBB0_1459:
	v_mov_b32_e32 v136, v1
	s_lshl_b32 s0, s0, 8
	v_mbcnt_lo_u32_b32 v136, -1, v136
	v_mbcnt_hi_u32_b32 v136, -1, v136
	s_add_i32 s0, s0, s43
	v_and_or_b32 v138, v136, 15, s0
	s_lshl_b32 s0, s1, 8
	v_lshrrev_b32_e32 v136, 2, v136
	v_and_or_b32 v136, v136, 12, s0
	v_or_b32_e32 v136, s44, v136
	v_lshlrev_b32_e32 v140, 12, v138
	v_lshl_add_u32 v136, v136, 2, v140
	v_add_u32_e32 v137, 0x10000, v136
	v_add_u32_e32 v138, 0x20000, v136
	v_add_u32_e32 v139, 0x30000, v136
	v_add_u32_e32 v140, 0x80000, v136
	v_add_u32_e32 v141, 0x90000, v136
	v_add_u32_e32 v144, 0xa0000, v136
	v_add_u32_e32 v145, 0xb0000, v136
	global_load_dwordx4 v[146:149], v136, s[4:5]
	global_load_dwordx4 v[150:153], v136, s[4:5] offset:64
	global_load_dwordx4 v[178:181], v136, s[4:5] offset:512
	global_load_dwordx4 v[182:185], v136, s[4:5] offset:576
	global_load_dwordx4 v[186:189], v137, s[4:5]
	global_load_dwordx4 v[190:193], v137, s[4:5] offset:64
	global_load_dwordx4 v[194:197], v137, s[4:5] offset:512
	global_load_dwordx4 v[210:213], v137, s[4:5] offset:576
	global_load_dwordx4 v[214:217], v138, s[4:5]
	global_load_dwordx4 v[218:221], v138, s[4:5] offset:64
	global_load_dwordx4 v[158:161], v138, s[4:5] offset:512
	global_load_dwordx4 v[162:165], v138, s[4:5] offset:576
	global_load_dwordx4 v[166:169], v139, s[4:5]
	global_load_dwordx4 v[170:173], v139, s[4:5] offset:64
	s_waitcnt vmcnt(13)
	v_pk_add_f32 v[128:129], v[128:129], v[148:149]
	v_pk_add_f32 v[126:127], v[126:127], v[146:147]
	global_store_dwordx4 v136, v[126:129], s[4:5]
	global_load_dwordx4 v[146:149], v139, s[4:5] offset:512
	s_waitcnt vmcnt(14)
	v_pk_add_f32 v[124:125], v[124:125], v[152:153]
	v_pk_add_f32 v[122:123], v[122:123], v[150:151]
	global_store_dwordx4 v136, v[122:125], s[4:5] offset:64
	global_load_dwordx4 v[150:153], v139, s[4:5] offset:576
	s_waitcnt vmcnt(15)
	v_pk_add_f32 v[120:121], v[120:121], v[180:181]
	v_pk_add_f32 v[118:119], v[118:119], v[178:179]
	global_store_dwordx4 v136, v[118:121], s[4:5] offset:512
	global_load_dwordx4 v[178:181], v140, s[4:5]
	s_waitcnt vmcnt(16)
	v_pk_add_f32 v[116:117], v[116:117], v[184:185]
	v_pk_add_f32 v[114:115], v[114:115], v[182:183]
	global_store_dwordx4 v136, v[114:117], s[4:5] offset:576
	global_load_dwordx4 v[182:185], v140, s[4:5] offset:64
	s_waitcnt vmcnt(17)
	v_pk_add_f32 v[112:113], v[112:113], v[188:189]
	v_pk_add_f32 v[110:111], v[110:111], v[186:187]
	global_store_dwordx4 v137, v[110:113], s[4:5]
	global_load_dwordx4 v[186:189], v140, s[4:5] offset:512
	s_waitcnt vmcnt(18)
	v_pk_add_f32 v[108:109], v[108:109], v[192:193]
	v_pk_add_f32 v[106:107], v[106:107], v[190:191]
	global_store_dwordx4 v137, v[106:109], s[4:5] offset:64
	global_load_dwordx4 v[190:193], v140, s[4:5] offset:576
	s_waitcnt vmcnt(19)
	v_pk_add_f32 v[104:105], v[104:105], v[196:197]
	v_pk_add_f32 v[102:103], v[102:103], v[194:195]
	global_store_dwordx4 v137, v[102:105], s[4:5] offset:512
	global_load_dwordx4 v[194:197], v141, s[4:5]
	s_waitcnt vmcnt(20)
	v_pk_add_f32 v[100:101], v[100:101], v[212:213]
	v_pk_add_f32 v[98:99], v[98:99], v[210:211]
	global_store_dwordx4 v137, v[98:101], s[4:5] offset:576
	global_load_dwordx4 v[210:213], v141, s[4:5] offset:64
	s_waitcnt vmcnt(21)
	v_pk_add_f32 v[96:97], v[96:97], v[216:217]
	v_pk_add_f32 v[94:95], v[94:95], v[214:215]
	global_store_dwordx4 v138, v[94:97], s[4:5]
	global_load_dwordx4 v[214:217], v141, s[4:5] offset:512
	s_waitcnt vmcnt(22)
	v_pk_add_f32 v[92:93], v[92:93], v[220:221]
	v_pk_add_f32 v[90:91], v[90:91], v[218:219]
	global_store_dwordx4 v138, v[90:93], s[4:5] offset:64
	global_load_dwordx4 v[218:221], v141, s[4:5] offset:576
	s_waitcnt vmcnt(23)
	v_pk_add_f32 v[88:89], v[88:89], v[160:161]
	v_pk_add_f32 v[86:87], v[86:87], v[158:159]
	global_store_dwordx4 v138, v[86:89], s[4:5] offset:512
	global_load_dwordx4 v[158:161], v144, s[4:5]
	s_waitcnt vmcnt(24)
;     DI void operator()(const Acc& acc, const Unit& u, int wr, int wc, int fr, int fq) const {
;         const int row0 = u.pm * BM + wr * 64 + fr, col0 = u.pn * BM + wc * 32 + 4 * fq;
; #pragma unroll
;         for (int ai = 0; ai < 2; ++ai)
; #pragma unroll
;             for (int m = 0; m < 4; ++m) {
;                 const size_t off = (size_t)(row0 + ai * HALF + m * 16) * ldc + col0;
; #pragma unroll
;                 for (int bj = 0; bj < 2; ++bj)
; #pragma unroll
;                     for (int n = 0; n < 2; ++n) { const f32x4 b = *(const f32x4*)(base + off + bj * HALF + n * 16); *(f32x4*)(out + off + bj * HALF + n * 16) = b + acc[ai][bj][m][n] * alpha; }
;                 asm volatile("" ::: "memory");
;             }
;     }
	v_pk_add_f32 v[84:85], v[84:85], v[164:165]
	v_pk_add_f32 v[82:83], v[82:83], v[162:163]
	global_store_dwordx4 v138, v[82:85], s[4:5] offset:576
	global_load_dwordx4 v[162:165], v144, s[4:5] offset:64
	s_waitcnt vmcnt(25)
	v_pk_add_f32 v[80:81], v[80:81], v[168:169]
	v_pk_add_f32 v[78:79], v[78:79], v[166:167]
	global_store_dwordx4 v139, v[78:81], s[4:5]
	global_load_dwordx4 v[166:169], v144, s[4:5] offset:512
	s_waitcnt vmcnt(26)
	v_pk_add_f32 v[76:77], v[76:77], v[172:173]
	v_pk_add_f32 v[74:75], v[74:75], v[170:171]
	global_store_dwordx4 v139, v[74:77], s[4:5] offset:64
	global_load_dwordx4 v[170:173], v144, s[4:5] offset:576
	s_waitcnt vmcnt(26)
	v_pk_add_f32 v[72:73], v[72:73], v[148:149]
	v_pk_add_f32 v[70:71], v[70:71], v[146:147]
	global_store_dwordx4 v139, v[70:73], s[4:5] offset:512
	global_load_dwordx4 v[146:149], v145, s[4:5]
	s_waitcnt vmcnt(26)
	v_pk_add_f32 v[68:69], v[68:69], v[152:153]
	v_pk_add_f32 v[66:67], v[66:67], v[150:151]
	global_store_dwordx4 v139, v[66:69], s[4:5] offset:576
	global_load_dwordx4 v[150:153], v145, s[4:5] offset:64
	s_waitcnt vmcnt(26)
	v_pk_add_f32 v[64:65], v[64:65], v[180:181]
	v_pk_add_f32 v[62:63], v[62:63], v[178:179]
	global_store_dwordx4 v140, v[62:65], s[4:5]
	global_load_dwordx4 v[178:181], v145, s[4:5] offset:512
	s_waitcnt vmcnt(26)
	v_pk_add_f32 v[60:61], v[60:61], v[184:185]
	v_pk_add_f32 v[58:59], v[58:59], v[182:183]
	global_store_dwordx4 v140, v[58:61], s[4:5] offset:64
	global_load_dwordx4 v[182:185], v145, s[4:5] offset:576
	s_waitcnt vmcnt(26)
	v_pk_add_f32 v[56:57], v[56:57], v[188:189]
	v_pk_add_f32 v[54:55], v[54:55], v[186:187]
	global_store_dwordx4 v140, v[54:57], s[4:5] offset:512
	s_waitcnt vmcnt(25)
	v_pk_add_f32 v[52:53], v[52:53], v[192:193]
	v_pk_add_f32 v[50:51], v[50:51], v[190:191]
	global_store_dwordx4 v140, v[50:53], s[4:5] offset:576
	s_waitcnt vmcnt(24)
	v_pk_add_f32 v[48:49], v[48:49], v[196:197]
	v_pk_add_f32 v[46:47], v[46:47], v[194:195]
	global_store_dwordx4 v141, v[46:49], s[4:5]
	s_waitcnt vmcnt(23)
	v_pk_add_f32 v[44:45], v[44:45], v[212:213]
	v_pk_add_f32 v[42:43], v[42:43], v[210:211]
	global_store_dwordx4 v141, v[42:45], s[4:5] offset:64
	s_waitcnt vmcnt(22)
	v_pk_add_f32 v[40:41], v[40:41], v[216:217]
	v_pk_add_f32 v[38:39], v[38:39], v[214:215]
	global_store_dwordx4 v141, v[38:41], s[4:5] offset:512
	s_waitcnt vmcnt(21)
	v_pk_add_f32 v[36:37], v[36:37], v[220:221]
	v_pk_add_f32 v[34:35], v[34:35], v[218:219]
	global_store_dwordx4 v141, v[34:37], s[4:5] offset:576
	s_waitcnt vmcnt(20)
	v_pk_add_f32 v[32:33], v[32:33], v[160:161]
	v_pk_add_f32 v[30:31], v[30:31], v[158:159]
	global_store_dwordx4 v144, v[30:33], s[4:5]
	s_waitcnt vmcnt(19)
	v_pk_add_f32 v[28:29], v[28:29], v[164:165]
	v_pk_add_f32 v[26:27], v[26:27], v[162:163]
	global_store_dwordx4 v144, v[26:29], s[4:5] offset:64
	s_waitcnt vmcnt(18)
	v_pk_add_f32 v[24:25], v[24:25], v[168:169]
	v_pk_add_f32 v[22:23], v[22:23], v[166:167]
	global_store_dwordx4 v144, v[22:25], s[4:5] offset:512
	s_waitcnt vmcnt(17)
	v_pk_add_f32 v[20:21], v[20:21], v[172:173]
	v_pk_add_f32 v[18:19], v[18:19], v[170:171]
	global_store_dwordx4 v144, v[18:21], s[4:5] offset:576
	s_waitcnt vmcnt(16)
	v_pk_add_f32 v[16:17], v[16:17], v[148:149]
	v_pk_add_f32 v[14:15], v[14:15], v[146:147]
	global_store_dwordx4 v145, v[14:17], s[4:5]
	s_waitcnt vmcnt(15)
	v_pk_add_f32 v[12:13], v[12:13], v[152:153]
	v_pk_add_f32 v[10:11], v[10:11], v[150:151]
	global_store_dwordx4 v145, v[10:13], s[4:5] offset:64
	s_waitcnt vmcnt(14)
	v_pk_add_f32 v[8:9], v[8:9], v[180:181]
	v_pk_add_f32 v[6:7], v[6:7], v[178:179]
	global_store_dwordx4 v145, v[6:9], s[4:5] offset:512
	s_waitcnt vmcnt(13)
	v_pk_add_f32 v[4:5], v[4:5], v[184:185]
	v_pk_add_f32 v[2:3], v[2:3], v[182:183]
	global_store_dwordx4 v145, v[2:5], s[4:5] offset:576
	s_mov_b64 s[0:1], -1
	s_andn2_b64 vcc, exec, s[2:3]
	s_cbranch_vccnz .LBB0_1448
	s_andn2_b64 vcc, exec, s[6:7]
	s_cbranch_vccnz .LBB0_1447
	s_barrier
	s_branch .LBB0_1447

; #define lds fresh_lds(lds0)
;     DI void operator()(const Acc& acc, const Unit& u, int wr, int wc, int fr, int fq) const {
;         const int row0 = u.pm * BM + wr * 64 + fr, col0 = u.pn * BM + wc * 32 + 4 * fq;
; #pragma unroll
;         for (int ai = 0; ai < 2; ++ai)
; #pragma unroll
;             for (int m = 0; m < 4; ++m) {
;                 const size_t off = (size_t)(row0 + ai * HALF + m * 16) * ldc + col0;
; #pragma unroll
;                 for (int bj = 0; bj < 2; ++bj)
; #pragma unroll
;                     for (int n = 0; n < 2; ++n) { const f32x4 b = *(const f32x4*)(base + off + bj * HALF + n * 16); *(f32x4*)(out + off + bj * HALF + n * 16) = b + acc[ai][bj][m][n] * alpha; }
;                 asm volatile("" ::: "memory");
;             }
;     }
; DI void ffn_gemms(LAS unsigned char* lds, cg::grid_group& grid, unsigned char* ws, const float* base, float* X, int G, int bid, int wv0) {
;     ...
;     { pg8::Gemm g{ACT, Wd, MTOK, DM, DFF, DFF, DFF}; pg8::StaticOrder S; S.init(MTOK, DM, G, bid); pg8::EpiResid E{rep == 0 ? base : X, X, DM, rep == 0 ? 0.5f : 0.f}; pg8::gemm_phase(lds, g, S, E, wv0); }
.LBB0_1634:
	v_mov_b32_e32 v136, v1
	s_lshl_b32 s0, s45, 8
	v_mbcnt_lo_u32_b32 v136, -1, v136
	v_mbcnt_hi_u32_b32 v136, -1, v136
	s_add_i32 s0, s0, s28
	v_and_or_b32 v138, v136, 15, s0
	s_lshl_b32 s0, s46, 8
	v_lshrrev_b32_e32 v136, 2, v136
	v_and_or_b32 v136, v136, 12, s0
	v_or_b32_e32 v136, s29, v136
	v_lshlrev_b32_e32 v140, 12, v138
	v_lshl_add_u32 v136, v136, 2, v140
	v_add_u32_e32 v137, 0x10000, v136
	v_add_u32_e32 v138, 0x20000, v136
	v_add_u32_e32 v139, 0x30000, v136
	v_add_u32_e32 v140, 0x80000, v136
	v_add_u32_e32 v141, 0x90000, v136
	v_add_u32_e32 v144, 0xa0000, v136
	v_add_u32_e32 v145, 0xb0000, v136
	global_load_dwordx4 v[146:149], v136, s[34:35]
	global_load_dwordx4 v[150:153], v136, s[34:35] offset:64
	global_load_dwordx4 v[178:181], v136, s[34:35] offset:512
	global_load_dwordx4 v[182:185], v136, s[34:35] offset:576
	global_load_dwordx4 v[186:189], v137, s[34:35]
	global_load_dwordx4 v[190:193], v137, s[34:35] offset:64
	global_load_dwordx4 v[194:197], v137, s[34:35] offset:512
	global_load_dwordx4 v[210:213], v137, s[34:35] offset:576
	global_load_dwordx4 v[214:217], v138, s[34:35]
	global_load_dwordx4 v[218:221], v138, s[34:35] offset:64
	global_load_dwordx4 v[158:161], v138, s[34:35] offset:512
	global_load_dwordx4 v[162:165], v138, s[34:35] offset:576
	global_load_dwordx4 v[166:169], v139, s[34:35]
	global_load_dwordx4 v[170:173], v139, s[34:35] offset:64
	s_waitcnt vmcnt(13)
	v_pk_fma_f32 v[128:129], v[128:129], 0.5, v[148:149] op_sel_hi:[1,0,1]
	v_pk_fma_f32 v[126:127], v[126:127], 0.5, v[146:147] op_sel_hi:[1,0,1]
	global_store_dwordx4 v136, v[126:129], s[34:35]
	global_load_dwordx4 v[146:149], v139, s[34:35] offset:512
	s_waitcnt vmcnt(14)
	v_pk_fma_f32 v[124:125], v[124:125], 0.5, v[152:153] op_sel_hi:[1,0,1]
	v_pk_fma_f32 v[122:123], v[122:123], 0.5, v[150:151] op_sel_hi:[1,0,1]
	global_store_dwordx4 v136, v[122:125], s[34:35] offset:64
	global_load_dwordx4 v[150:153], v139, s[34:35] offset:576
	s_waitcnt vmcnt(15)
	v_pk_fma_f32 v[120:121], v[120:121], 0.5, v[180:181] op_sel_hi:[1,0,1]
	v_pk_fma_f32 v[118:119], v[118:119], 0.5, v[178:179] op_sel_hi:[1,0,1]
	global_store_dwordx4 v136, v[118:121], s[34:35] offset:512
	global_load_dwordx4 v[178:181], v140, s[34:35]
	s_waitcnt vmcnt(16)
	v_pk_fma_f32 v[116:117], v[116:117], 0.5, v[184:185] op_sel_hi:[1,0,1]
	v_pk_fma_f32 v[114:115], v[114:115], 0.5, v[182:183] op_sel_hi:[1,0,1]
	global_store_dwordx4 v136, v[114:117], s[34:35] offset:576
	global_load_dwordx4 v[182:185], v140, s[34:35] offset:64
	s_waitcnt vmcnt(17)
	v_pk_fma_f32 v[112:113], v[112:113], 0.5, v[188:189] op_sel_hi:[1,0,1]
	v_pk_fma_f32 v[110:111], v[110:111], 0.5, v[186:187] op_sel_hi:[1,0,1]
	global_store_dwordx4 v137, v[110:113], s[34:35]
	global_load_dwordx4 v[186:189], v140, s[34:35] offset:512
	s_waitcnt vmcnt(18)
	v_pk_fma_f32 v[108:109], v[108:109], 0.5, v[192:193] op_sel_hi:[1,0,1]
	v_pk_fma_f32 v[106:107], v[106:107], 0.5, v[190:191] op_sel_hi:[1,0,1]
	global_store_dwordx4 v137, v[106:109], s[34:35] offset:64
	global_load_dwordx4 v[190:193], v140, s[34:35] offset:576
	s_waitcnt vmcnt(19)
	v_pk_fma_f32 v[104:105], v[104:105], 0.5, v[196:197] op_sel_hi:[1,0,1]
	v_pk_fma_f32 v[102:103], v[102:103], 0.5, v[194:195] op_sel_hi:[1,0,1]
	global_store_dwordx4 v137, v[102:105], s[34:35] offset:512
	global_load_dwordx4 v[194:197], v141, s[34:35]
	s_waitcnt vmcnt(20)
	v_pk_fma_f32 v[100:101], v[100:101], 0.5, v[212:213] op_sel_hi:[1,0,1]
	v_pk_fma_f32 v[98:99], v[98:99], 0.5, v[210:211] op_sel_hi:[1,0,1]
	global_store_dwordx4 v137, v[98:101], s[34:35] offset:576
	global_load_dwordx4 v[210:213], v141, s[34:35] offset:64
	s_waitcnt vmcnt(21)
	v_pk_fma_f32 v[96:97], v[96:97], 0.5, v[216:217] op_sel_hi:[1,0,1]
	v_pk_fma_f32 v[94:95], v[94:95], 0.5, v[214:215] op_sel_hi:[1,0,1]
	global_store_dwordx4 v138, v[94:97], s[34:35]
	global_load_dwordx4 v[214:217], v141, s[34:35] offset:512
	s_waitcnt vmcnt(22)
	v_pk_fma_f32 v[92:93], v[92:93], 0.5, v[220:221] op_sel_hi:[1,0,1]
	v_pk_fma_f32 v[90:91], v[90:91], 0.5, v[218:219] op_sel_hi:[1,0,1]
	global_store_dwordx4 v138, v[90:93], s[34:35] offset:64
	global_load_dwordx4 v[218:221], v141, s[34:35] offset:576
	s_waitcnt vmcnt(23)
	v_pk_fma_f32 v[88:89], v[88:89], 0.5, v[160:161] op_sel_hi:[1,0,1]
	v_pk_fma_f32 v[86:87], v[86:87], 0.5, v[158:159] op_sel_hi:[1,0,1]
	global_store_dwordx4 v138, v[86:89], s[34:35] offset:512
	global_load_dwordx4 v[158:161], v144, s[34:35]
	s_waitcnt vmcnt(24)
	v_pk_fma_f32 v[84:85], v[84:85], 0.5, v[164:165] op_sel_hi:[1,0,1]
	v_pk_fma_f32 v[82:83], v[82:83], 0.5, v[162:163] op_sel_hi:[1,0,1]
	global_store_dwordx4 v138, v[82:85], s[34:35] offset:576
	global_load_dwordx4 v[162:165], v144, s[34:35] offset:64
	s_waitcnt vmcnt(25)
;     DI void operator()(const Acc& acc, const Unit& u, int wr, int wc, int fr, int fq) const {
;         const int row0 = u.pm * BM + wr * 64 + fr, col0 = u.pn * BM + wc * 32 + 4 * fq;
; #pragma unroll
;         for (int ai = 0; ai < 2; ++ai)
; #pragma unroll
;             for (int m = 0; m < 4; ++m) {
;                 const size_t off = (size_t)(row0 + ai * HALF + m * 16) * ldc + col0;
; #pragma unroll
;                 for (int bj = 0; bj < 2; ++bj)
; #pragma unroll
;                     for (int n = 0; n < 2; ++n) { const f32x4 b = *(const f32x4*)(base + off + bj * HALF + n * 16); *(f32x4*)(out + off + bj * HALF + n * 16) = b + acc[ai][bj][m][n] * alpha; }
;                 asm volatile("" ::: "memory");
;             }
;     }
	v_pk_fma_f32 v[80:81], v[80:81], 0.5, v[168:169] op_sel_hi:[1,0,1]
	v_pk_fma_f32 v[78:79], v[78:79], 0.5, v[166:167] op_sel_hi:[1,0,1]
	global_store_dwordx4 v139, v[78:81], s[34:35]
	global_load_dwordx4 v[166:169], v144, s[34:35] offset:512
	s_waitcnt vmcnt(26)
	v_pk_fma_f32 v[76:77], v[76:77], 0.5, v[172:173] op_sel_hi:[1,0,1]
	v_pk_fma_f32 v[74:75], v[74:75], 0.5, v[170:171] op_sel_hi:[1,0,1]
	global_store_dwordx4 v139, v[74:77], s[34:35] offset:64
	global_load_dwordx4 v[170:173], v144, s[34:35] offset:576
	s_waitcnt vmcnt(26)
	v_pk_fma_f32 v[72:73], v[72:73], 0.5, v[148:149] op_sel_hi:[1,0,1]
	v_pk_fma_f32 v[70:71], v[70:71], 0.5, v[146:147] op_sel_hi:[1,0,1]
	global_store_dwordx4 v139, v[70:73], s[34:35] offset:512
	global_load_dwordx4 v[146:149], v145, s[34:35]
	s_waitcnt vmcnt(26)
	v_pk_fma_f32 v[68:69], v[68:69], 0.5, v[152:153] op_sel_hi:[1,0,1]
	v_pk_fma_f32 v[66:67], v[66:67], 0.5, v[150:151] op_sel_hi:[1,0,1]
	global_store_dwordx4 v139, v[66:69], s[34:35] offset:576
	global_load_dwordx4 v[150:153], v145, s[34:35] offset:64
	s_waitcnt vmcnt(26)
	v_pk_fma_f32 v[64:65], v[64:65], 0.5, v[180:181] op_sel_hi:[1,0,1]
	v_pk_fma_f32 v[62:63], v[62:63], 0.5, v[178:179] op_sel_hi:[1,0,1]
	global_store_dwordx4 v140, v[62:65], s[34:35]
	global_load_dwordx4 v[178:181], v145, s[34:35] offset:512
	s_waitcnt vmcnt(26)
	v_pk_fma_f32 v[60:61], v[60:61], 0.5, v[184:185] op_sel_hi:[1,0,1]
	v_pk_fma_f32 v[58:59], v[58:59], 0.5, v[182:183] op_sel_hi:[1,0,1]
	global_store_dwordx4 v140, v[58:61], s[34:35] offset:64
	global_load_dwordx4 v[182:185], v145, s[34:35] offset:576
	s_waitcnt vmcnt(26)
	v_pk_fma_f32 v[56:57], v[56:57], 0.5, v[188:189] op_sel_hi:[1,0,1]
	v_pk_fma_f32 v[54:55], v[54:55], 0.5, v[186:187] op_sel_hi:[1,0,1]
	global_store_dwordx4 v140, v[54:57], s[34:35] offset:512
	s_waitcnt vmcnt(25)
	v_pk_fma_f32 v[52:53], v[52:53], 0.5, v[192:193] op_sel_hi:[1,0,1]
	v_pk_fma_f32 v[50:51], v[50:51], 0.5, v[190:191] op_sel_hi:[1,0,1]
	global_store_dwordx4 v140, v[50:53], s[34:35] offset:576
	s_waitcnt vmcnt(24)
	v_pk_fma_f32 v[48:49], v[48:49], 0.5, v[196:197] op_sel_hi:[1,0,1]
	v_pk_fma_f32 v[46:47], v[46:47], 0.5, v[194:195] op_sel_hi:[1,0,1]
	global_store_dwordx4 v141, v[46:49], s[34:35]
	s_waitcnt vmcnt(23)
	v_pk_fma_f32 v[44:45], v[44:45], 0.5, v[212:213] op_sel_hi:[1,0,1]
	v_pk_fma_f32 v[42:43], v[42:43], 0.5, v[210:211] op_sel_hi:[1,0,1]
	global_store_dwordx4 v141, v[42:45], s[34:35] offset:64
	s_waitcnt vmcnt(22)
	v_pk_fma_f32 v[40:41], v[40:41], 0.5, v[216:217] op_sel_hi:[1,0,1]
	v_pk_fma_f32 v[38:39], v[38:39], 0.5, v[214:215] op_sel_hi:[1,0,1]
	global_store_dwordx4 v141, v[38:41], s[34:35] offset:512
	s_waitcnt vmcnt(21)
	v_pk_fma_f32 v[36:37], v[36:37], 0.5, v[220:221] op_sel_hi:[1,0,1]
	v_pk_fma_f32 v[34:35], v[34:35], 0.5, v[218:219] op_sel_hi:[1,0,1]
	global_store_dwordx4 v141, v[34:37], s[34:35] offset:576
	s_waitcnt vmcnt(20)
	v_pk_fma_f32 v[32:33], v[32:33], 0.5, v[160:161] op_sel_hi:[1,0,1]
	v_pk_fma_f32 v[30:31], v[30:31], 0.5, v[158:159] op_sel_hi:[1,0,1]
	global_store_dwordx4 v144, v[30:33], s[34:35]
	s_waitcnt vmcnt(19)
	v_pk_fma_f32 v[28:29], v[28:29], 0.5, v[164:165] op_sel_hi:[1,0,1]
	v_pk_fma_f32 v[26:27], v[26:27], 0.5, v[162:163] op_sel_hi:[1,0,1]
	global_store_dwordx4 v144, v[26:29], s[34:35] offset:64
	s_waitcnt vmcnt(18)
	v_pk_fma_f32 v[24:25], v[24:25], 0.5, v[168:169] op_sel_hi:[1,0,1]
	v_pk_fma_f32 v[22:23], v[22:23], 0.5, v[166:167] op_sel_hi:[1,0,1]
	global_store_dwordx4 v144, v[22:25], s[34:35] offset:512
	s_waitcnt vmcnt(17)
	v_pk_fma_f32 v[20:21], v[20:21], 0.5, v[172:173] op_sel_hi:[1,0,1]
	v_pk_fma_f32 v[18:19], v[18:19], 0.5, v[170:171] op_sel_hi:[1,0,1]
	global_store_dwordx4 v144, v[18:21], s[34:35] offset:576
	s_waitcnt vmcnt(16)
	v_pk_fma_f32 v[16:17], v[16:17], 0.5, v[148:149] op_sel_hi:[1,0,1]
	v_pk_fma_f32 v[14:15], v[14:15], 0.5, v[146:147] op_sel_hi:[1,0,1]
	global_store_dwordx4 v145, v[14:17], s[34:35]
	s_waitcnt vmcnt(15)
	v_pk_fma_f32 v[12:13], v[12:13], 0.5, v[152:153] op_sel_hi:[1,0,1]
	v_pk_fma_f32 v[10:11], v[10:11], 0.5, v[150:151] op_sel_hi:[1,0,1]
	global_store_dwordx4 v145, v[10:13], s[34:35] offset:64
	s_waitcnt vmcnt(14)
	v_pk_fma_f32 v[8:9], v[8:9], 0.5, v[180:181] op_sel_hi:[1,0,1]
	v_pk_fma_f32 v[6:7], v[6:7], 0.5, v[178:179] op_sel_hi:[1,0,1]
	global_store_dwordx4 v145, v[6:9], s[34:35] offset:512
	s_waitcnt vmcnt(13)
	v_pk_fma_f32 v[4:5], v[4:5], 0.5, v[184:185] op_sel_hi:[1,0,1]
	v_pk_fma_f32 v[2:3], v[2:3], 0.5, v[182:183] op_sel_hi:[1,0,1]
	global_store_dwordx4 v145, v[2:5], s[34:35] offset:576
	s_mov_b64 s[0:1], -1
	s_and_b64 vcc, exec, s[2:3]
	s_cbranch_vccnz .LBB0_1619
	s_andn2_b64 vcc, exec, s[6:7]
	s_cbranch_vccnz .LBB0_1618
	s_barrier
	s_branch .LBB0_1618
